# plus: gather epilogue (residual, final rmsnorm, stores) rewritten by hand: 24 loads issued together, DPP row reduce
# speedup vs baseline: 1.0222x; 1.0222x over previous
; DEVI float4 ldbf4(const uint16_t* p) { const uint2 v = *(const uint2*)p; return make_float4(bflo(v.x), bfhi(v.x), bflo(v.y), bfhi(v.y)); }
; __device__ void phase_gather(const P& p, int vb, int nvb, char* smem) {
;     ...
;     asm volatile("" ::: "memory");
;     float ss = 0.f;
; #pragma unroll
;     for (int i = 0; i < 4; i++) {
; #pragma unroll
;       for (int q = 0; q < 4; q++) {
;         const float4 a = ldbf4(hr + i * 256 + 16 * j + 4 * q);
;         const float v0 = acc[i * 8 + q * 2].x + a.x, v1 = acc[i * 8 + q * 2].y + a.y, v2 = acc[i * 8 + q * 2 + 1].x + a.z, v3 = acc[i * 8 + q * 2 + 1].y + a.w;
;         acc[i * 8 + q * 2] = f32x2{v0, v1}; acc[i * 8 + q * 2 + 1] = f32x2{v2, v3};
;         ss += v0 * v0 + v1 * v1 + v2 * v2 + v3 * v3;
;       }
;       __builtin_amdgcn_sched_barrier(0);
;     }
;     const float rstd = rsqrtf(wsum16(ss) * (1.f / 1024.f) + EPS);
.Lgv_f_x:
	global_load_dwordx4 v[150:153], v[28:29], off
	global_load_dwordx4 v[154:157], v[28:29], off offset:16
	global_load_dwordx4 v[158:161], v[28:29], off offset:512
	global_load_dwordx4 v[162:165], v[28:29], off offset:528
	global_load_dwordx4 v[166:169], v[28:29], off offset:1024
	global_load_dwordx4 v[170:173], v[28:29], off offset:1040
	global_load_dwordx4 v[174:177], v[28:29], off offset:1536
	global_load_dwordx4 v[178:181], v[28:29], off offset:1552
	global_load_dwordx4 v[182:185], v[22:23], off
	global_load_dwordx4 v[186:189], v[22:23], off offset:16
	global_load_dwordx4 v[190:193], v[22:23], off offset:32
	global_load_dwordx4 v[194:197], v[22:23], off offset:48
	global_load_dwordx4 v[198:201], v[22:23], off offset:1024
	global_load_dwordx4 v[202:205], v[22:23], off offset:1040
	global_load_dwordx4 v[206:209], v[22:23], off offset:1056
	global_load_dwordx4 v[210:213], v[22:23], off offset:1072
	global_load_dwordx4 v[214:217], v[22:23], off offset:2048
	global_load_dwordx4 v[218:221], v[22:23], off offset:2064
	global_load_dwordx4 v[222:225], v[22:23], off offset:2080
	global_load_dwordx4 v[226:229], v[22:23], off offset:2096
	global_load_dwordx4 v[230:233], v[22:23], off offset:3072
	global_load_dwordx4 v[234:237], v[22:23], off offset:3088
	global_load_dwordx4 v[238:241], v[22:23], off offset:3104
	global_load_dwordx4 v[242:245], v[22:23], off offset:3120
	v_lshl_add_u64 v[246:247], v[30:31], 2, v[26:27]
	s_waitcnt vmcnt(23)
	v_lshlrev_b32_e32 v2, 16, v150
	v_and_b32_e32 v3, 0xffff0000, v150
	v_pk_add_f32 v[94:95], v[94:95], v[2:3]
	v_lshlrev_b32_e32 v4, 16, v151
	v_and_b32_e32 v5, 0xffff0000, v151
	v_pk_add_f32 v[92:93], v[92:93], v[4:5]
	v_pk_mul_f32 v[0:1], v[94:95], v[94:95]
	v_lshlrev_b32_e32 v2, 16, v152
	v_and_b32_e32 v3, 0xffff0000, v152
	v_pk_add_f32 v[90:91], v[90:91], v[2:3]
	v_pk_fma_f32 v[0:1], v[92:93], v[92:93], v[0:1]
	v_lshlrev_b32_e32 v4, 16, v153
	v_and_b32_e32 v5, 0xffff0000, v153
	v_pk_add_f32 v[88:89], v[88:89], v[4:5]
	v_pk_fma_f32 v[0:1], v[90:91], v[90:91], v[0:1]
	s_nop 0
	v_pk_fma_f32 v[0:1], v[88:89], v[88:89], v[0:1]
	s_waitcnt vmcnt(22)
	v_lshlrev_b32_e32 v2, 16, v154
	v_and_b32_e32 v3, 0xffff0000, v154
	v_pk_add_f32 v[86:87], v[86:87], v[2:3]
	v_lshlrev_b32_e32 v4, 16, v155
	v_and_b32_e32 v5, 0xffff0000, v155
	v_pk_add_f32 v[84:85], v[84:85], v[4:5]
	v_pk_fma_f32 v[0:1], v[86:87], v[86:87], v[0:1]
	v_lshlrev_b32_e32 v2, 16, v156
	v_and_b32_e32 v3, 0xffff0000, v156
	v_pk_add_f32 v[82:83], v[82:83], v[2:3]
	v_pk_fma_f32 v[0:1], v[84:85], v[84:85], v[0:1]
	v_lshlrev_b32_e32 v4, 16, v157
	v_and_b32_e32 v5, 0xffff0000, v157
	v_pk_add_f32 v[80:81], v[80:81], v[4:5]
	v_pk_fma_f32 v[0:1], v[82:83], v[82:83], v[0:1]
	s_nop 0
	v_pk_fma_f32 v[0:1], v[80:81], v[80:81], v[0:1]
	s_waitcnt vmcnt(21)
	v_lshlrev_b32_e32 v2, 16, v158
	v_and_b32_e32 v3, 0xffff0000, v158
	v_pk_add_f32 v[78:79], v[78:79], v[2:3]
	v_lshlrev_b32_e32 v4, 16, v159
	v_and_b32_e32 v5, 0xffff0000, v159
	v_pk_add_f32 v[76:77], v[76:77], v[4:5]
	v_pk_fma_f32 v[0:1], v[78:79], v[78:79], v[0:1]
	v_lshlrev_b32_e32 v2, 16, v160
	v_and_b32_e32 v3, 0xffff0000, v160
	v_pk_add_f32 v[74:75], v[74:75], v[2:3]
	v_pk_fma_f32 v[0:1], v[76:77], v[76:77], v[0:1]
	v_lshlrev_b32_e32 v4, 16, v161
	v_and_b32_e32 v5, 0xffff0000, v161
	v_pk_add_f32 v[72:73], v[72:73], v[4:5]
	v_pk_fma_f32 v[0:1], v[74:75], v[74:75], v[0:1]
	s_nop 0
	v_pk_fma_f32 v[0:1], v[72:73], v[72:73], v[0:1]
	s_waitcnt vmcnt(20)
	v_lshlrev_b32_e32 v2, 16, v162
	v_and_b32_e32 v3, 0xffff0000, v162
	v_pk_add_f32 v[70:71], v[70:71], v[2:3]
	v_lshlrev_b32_e32 v4, 16, v163
	v_and_b32_e32 v5, 0xffff0000, v163
	v_pk_add_f32 v[68:69], v[68:69], v[4:5]
	v_pk_fma_f32 v[0:1], v[70:71], v[70:71], v[0:1]
	v_lshlrev_b32_e32 v2, 16, v164
	v_and_b32_e32 v3, 0xffff0000, v164
	v_pk_add_f32 v[66:67], v[66:67], v[2:3]
	v_pk_fma_f32 v[0:1], v[68:69], v[68:69], v[0:1]
	v_lshlrev_b32_e32 v4, 16, v165
	v_and_b32_e32 v5, 0xffff0000, v165
	v_pk_add_f32 v[62:63], v[62:63], v[4:5]
	v_pk_fma_f32 v[0:1], v[66:67], v[66:67], v[0:1]
	s_nop 0
	v_pk_fma_f32 v[0:1], v[62:63], v[62:63], v[0:1]
	s_waitcnt vmcnt(19)
	v_lshlrev_b32_e32 v2, 16, v166
	v_and_b32_e32 v3, 0xffff0000, v166
	v_pk_add_f32 v[64:65], v[64:65], v[2:3]
	v_lshlrev_b32_e32 v4, 16, v167
	v_and_b32_e32 v5, 0xffff0000, v167
	v_pk_add_f32 v[60:61], v[60:61], v[4:5]
	v_pk_fma_f32 v[0:1], v[64:65], v[64:65], v[0:1]
	v_lshlrev_b32_e32 v2, 16, v168
	v_and_b32_e32 v3, 0xffff0000, v168
	v_pk_add_f32 v[58:59], v[58:59], v[2:3]
	v_pk_fma_f32 v[0:1], v[60:61], v[60:61], v[0:1]
	v_lshlrev_b32_e32 v4, 16, v169
	v_and_b32_e32 v5, 0xffff0000, v169
	v_pk_add_f32 v[56:57], v[56:57], v[4:5]
	v_pk_fma_f32 v[0:1], v[58:59], v[58:59], v[0:1]
	s_nop 0
	v_pk_fma_f32 v[0:1], v[56:57], v[56:57], v[0:1]
	s_waitcnt vmcnt(18)
	v_lshlrev_b32_e32 v2, 16, v170
	v_and_b32_e32 v3, 0xffff0000, v170
	v_pk_add_f32 v[54:55], v[54:55], v[2:3]
	v_lshlrev_b32_e32 v4, 16, v171
	v_and_b32_e32 v5, 0xffff0000, v171
	v_pk_add_f32 v[52:53], v[52:53], v[4:5]
	v_pk_fma_f32 v[0:1], v[54:55], v[54:55], v[0:1]
	v_lshlrev_b32_e32 v2, 16, v172
	v_and_b32_e32 v3, 0xffff0000, v172
	v_pk_add_f32 v[50:51], v[50:51], v[2:3]
	v_pk_fma_f32 v[0:1], v[52:53], v[52:53], v[0:1]
	v_lshlrev_b32_e32 v4, 16, v173
	v_and_b32_e32 v5, 0xffff0000, v173
	v_pk_add_f32 v[48:49], v[48:49], v[4:5]
	v_pk_fma_f32 v[0:1], v[50:51], v[50:51], v[0:1]
	s_nop 0
	v_pk_fma_f32 v[0:1], v[48:49], v[48:49], v[0:1]
	s_waitcnt vmcnt(17)
; DEVI float4 ldbf4(const uint16_t* p) { const uint2 v = *(const uint2*)p; return make_float4(bflo(v.x), bfhi(v.x), bflo(v.y), bfhi(v.y)); }
; __device__ void phase_gather(const P& p, int vb, int nvb, char* smem) {
;     ...
;     asm volatile("" ::: "memory");
;     float ss = 0.f;
; #pragma unroll
;     for (int i = 0; i < 4; i++) {
; #pragma unroll
;       for (int q = 0; q < 4; q++) {
;         const float4 a = ldbf4(hr + i * 256 + 16 * j + 4 * q);
;         const float v0 = acc[i * 8 + q * 2].x + a.x, v1 = acc[i * 8 + q * 2].y + a.y, v2 = acc[i * 8 + q * 2 + 1].x + a.z, v3 = acc[i * 8 + q * 2 + 1].y + a.w;
;         acc[i * 8 + q * 2] = f32x2{v0, v1}; acc[i * 8 + q * 2 + 1] = f32x2{v2, v3};
;         ss += v0 * v0 + v1 * v1 + v2 * v2 + v3 * v3;
;       }
;       __builtin_amdgcn_sched_barrier(0);
;     }
;     const float rstd = rsqrtf(wsum16(ss) * (1.f / 1024.f) + EPS);
;     float* orow = p.out + (size_t)rr * DM;
; #pragma unroll
;     for (int i = 0; i < 4; i++) {
; #pragma unroll
;       for (int q = 0; q < 4; q++) {
;         const float4 ga = *(const float4*)(gfin + i * 256 + 16 * j + 4 * q);
;         *(float4*)(orow + i * 256 + 16 * j + 4 * q) =
;             make_float4(acc[i * 8 + q * 2].x * rstd * ga.x, acc[i * 8 + q * 2].y * rstd * ga.y, acc[i * 8 + q * 2 + 1].x * rstd * ga.z, acc[i * 8 + q * 2 + 1].y * rstd * ga.w);
;       }
;       __builtin_amdgcn_sched_barrier(0);
;     }
	v_lshlrev_b32_e32 v2, 16, v174
	v_and_b32_e32 v3, 0xffff0000, v174
	v_pk_add_f32 v[46:47], v[46:47], v[2:3]
	v_lshlrev_b32_e32 v4, 16, v175
	v_and_b32_e32 v5, 0xffff0000, v175
	v_pk_add_f32 v[44:45], v[44:45], v[4:5]
	v_pk_fma_f32 v[0:1], v[46:47], v[46:47], v[0:1]
	v_lshlrev_b32_e32 v2, 16, v176
	v_and_b32_e32 v3, 0xffff0000, v176
	v_pk_add_f32 v[42:43], v[42:43], v[2:3]
	v_pk_fma_f32 v[0:1], v[44:45], v[44:45], v[0:1]
	v_lshlrev_b32_e32 v4, 16, v177
	v_and_b32_e32 v5, 0xffff0000, v177
	v_pk_add_f32 v[40:41], v[40:41], v[4:5]
	v_pk_fma_f32 v[0:1], v[42:43], v[42:43], v[0:1]
	s_nop 0
	v_pk_fma_f32 v[0:1], v[40:41], v[40:41], v[0:1]
	s_waitcnt vmcnt(16)
	v_lshlrev_b32_e32 v2, 16, v178
	v_and_b32_e32 v3, 0xffff0000, v178
	v_pk_add_f32 v[38:39], v[38:39], v[2:3]
	v_lshlrev_b32_e32 v4, 16, v179
	v_and_b32_e32 v5, 0xffff0000, v179
	v_pk_add_f32 v[36:37], v[36:37], v[4:5]
	v_pk_fma_f32 v[0:1], v[38:39], v[38:39], v[0:1]
	v_lshlrev_b32_e32 v2, 16, v180
	v_and_b32_e32 v3, 0xffff0000, v180
	v_pk_add_f32 v[34:35], v[34:35], v[2:3]
	v_pk_fma_f32 v[0:1], v[36:37], v[36:37], v[0:1]
	v_lshlrev_b32_e32 v4, 16, v181
	v_and_b32_e32 v5, 0xffff0000, v181
	v_pk_add_f32 v[32:33], v[32:33], v[4:5]
	v_pk_fma_f32 v[0:1], v[34:35], v[34:35], v[0:1]
	s_nop 0
	v_pk_fma_f32 v[0:1], v[32:33], v[32:33], v[0:1]
	s_nop 0
	v_add_f32_e32 v12, v0, v1
	s_nop 1
	v_add_f32_dpp v12, v12, v12 row_ror:8 row_mask:0xf bank_mask:0xf
	s_nop 1
	v_add_f32_dpp v12, v12, v12 row_ror:4 row_mask:0xf bank_mask:0xf
	s_nop 1
	v_add_f32_dpp v12, v12, v12 row_ror:2 row_mask:0xf bank_mask:0xf
	s_nop 1
	v_add_f32_dpp v12, v12, v12 row_ror:1 row_mask:0xf bank_mask:0xf
	s_nop 0
	v_fmamk_f32 v12, v12, 0x3a800000, v143
	v_mul_f32_e32 v2, 0x4b800000, v12
	v_cmp_gt_f32_e64 s[20:21], s29, v12
	s_nop 1
	v_cndmask_b32_e64 v12, v12, v2, s[20:21]
	v_rsq_f32_e32 v12, v12
	s_nop 0
	v_mul_f32_e32 v2, 0x45800000, v12
	v_cndmask_b32_e64 v12, v12, v2, s[20:21]
	s_waitcnt vmcnt(15)
	v_pk_mul_f32 v[4:5], v[94:95], v[12:13] op_sel_hi:[1,0]
	v_pk_mul_f32 v[6:7], v[92:93], v[12:13] op_sel_hi:[1,0]
	v_pk_mul_f32 v[4:5], v[4:5], v[182:183]
	v_pk_mul_f32 v[6:7], v[6:7], v[184:185]
	s_nop 0
	global_store_dwordx4 v[246:247], v[4:7], off
	s_waitcnt vmcnt(15)
	v_pk_mul_f32 v[8:9], v[90:91], v[12:13] op_sel_hi:[1,0]
	v_pk_mul_f32 v[10:11], v[88:89], v[12:13] op_sel_hi:[1,0]
	v_pk_mul_f32 v[8:9], v[8:9], v[186:187]
	v_pk_mul_f32 v[10:11], v[10:11], v[188:189]
	s_nop 0
	global_store_dwordx4 v[246:247], v[8:11], off offset:16
	s_waitcnt vmcnt(15)
	v_pk_mul_f32 v[4:5], v[86:87], v[12:13] op_sel_hi:[1,0]
	v_pk_mul_f32 v[6:7], v[84:85], v[12:13] op_sel_hi:[1,0]
	v_pk_mul_f32 v[4:5], v[4:5], v[190:191]
	v_pk_mul_f32 v[6:7], v[6:7], v[192:193]
	s_nop 0
	global_store_dwordx4 v[246:247], v[4:7], off offset:32
	s_waitcnt vmcnt(15)
	v_pk_mul_f32 v[8:9], v[82:83], v[12:13] op_sel_hi:[1,0]
	v_pk_mul_f32 v[10:11], v[80:81], v[12:13] op_sel_hi:[1,0]
	v_pk_mul_f32 v[8:9], v[8:9], v[194:195]
	v_pk_mul_f32 v[10:11], v[10:11], v[196:197]
	s_nop 0
	global_store_dwordx4 v[246:247], v[8:11], off offset:48
	s_waitcnt vmcnt(15)
	v_pk_mul_f32 v[4:5], v[78:79], v[12:13] op_sel_hi:[1,0]
	v_pk_mul_f32 v[6:7], v[76:77], v[12:13] op_sel_hi:[1,0]
	v_pk_mul_f32 v[4:5], v[4:5], v[198:199]
	v_pk_mul_f32 v[6:7], v[6:7], v[200:201]
	s_nop 0
	global_store_dwordx4 v[246:247], v[4:7], off offset:1024
	s_waitcnt vmcnt(15)
	v_pk_mul_f32 v[8:9], v[74:75], v[12:13] op_sel_hi:[1,0]
	v_pk_mul_f32 v[10:11], v[72:73], v[12:13] op_sel_hi:[1,0]
	v_pk_mul_f32 v[8:9], v[8:9], v[202:203]
	v_pk_mul_f32 v[10:11], v[10:11], v[204:205]
	s_nop 0
	global_store_dwordx4 v[246:247], v[8:11], off offset:1040
	s_waitcnt vmcnt(15)
	v_pk_mul_f32 v[4:5], v[70:71], v[12:13] op_sel_hi:[1,0]
	v_pk_mul_f32 v[6:7], v[68:69], v[12:13] op_sel_hi:[1,0]
	v_pk_mul_f32 v[4:5], v[4:5], v[206:207]
	v_pk_mul_f32 v[6:7], v[6:7], v[208:209]
	s_nop 0
	global_store_dwordx4 v[246:247], v[4:7], off offset:1056
	s_waitcnt vmcnt(15)
	v_pk_mul_f32 v[8:9], v[66:67], v[12:13] op_sel_hi:[1,0]
	v_pk_mul_f32 v[10:11], v[62:63], v[12:13] op_sel_hi:[1,0]
	v_pk_mul_f32 v[8:9], v[8:9], v[210:211]
	v_pk_mul_f32 v[10:11], v[10:11], v[212:213]
	s_nop 0
	global_store_dwordx4 v[246:247], v[8:11], off offset:1072
	s_waitcnt vmcnt(15)
	v_pk_mul_f32 v[4:5], v[64:65], v[12:13] op_sel_hi:[1,0]
	v_pk_mul_f32 v[6:7], v[60:61], v[12:13] op_sel_hi:[1,0]
	v_pk_mul_f32 v[4:5], v[4:5], v[214:215]
	v_pk_mul_f32 v[6:7], v[6:7], v[216:217]
	s_nop 0
	global_store_dwordx4 v[246:247], v[4:7], off offset:2048
	s_waitcnt vmcnt(15)
	v_pk_mul_f32 v[8:9], v[58:59], v[12:13] op_sel_hi:[1,0]
	v_pk_mul_f32 v[10:11], v[56:57], v[12:13] op_sel_hi:[1,0]
	v_pk_mul_f32 v[8:9], v[8:9], v[218:219]
	v_pk_mul_f32 v[10:11], v[10:11], v[220:221]
	s_nop 0
	global_store_dwordx4 v[246:247], v[8:11], off offset:2064
	s_waitcnt vmcnt(15)
	v_pk_mul_f32 v[4:5], v[54:55], v[12:13] op_sel_hi:[1,0]
	v_pk_mul_f32 v[6:7], v[52:53], v[12:13] op_sel_hi:[1,0]
	v_pk_mul_f32 v[4:5], v[4:5], v[222:223]
	v_pk_mul_f32 v[6:7], v[6:7], v[224:225]
	s_nop 0
	global_store_dwordx4 v[246:247], v[4:7], off offset:2080
	s_waitcnt vmcnt(15)
	v_pk_mul_f32 v[8:9], v[50:51], v[12:13] op_sel_hi:[1,0]
	v_pk_mul_f32 v[10:11], v[48:49], v[12:13] op_sel_hi:[1,0]
	v_pk_mul_f32 v[8:9], v[8:9], v[226:227]
	v_pk_mul_f32 v[10:11], v[10:11], v[228:229]
	s_nop 0
	global_store_dwordx4 v[246:247], v[8:11], off offset:2096
	s_waitcnt vmcnt(15)
	v_pk_mul_f32 v[4:5], v[46:47], v[12:13] op_sel_hi:[1,0]
	v_pk_mul_f32 v[6:7], v[44:45], v[12:13] op_sel_hi:[1,0]
	v_pk_mul_f32 v[4:5], v[4:5], v[230:231]
	v_pk_mul_f32 v[6:7], v[6:7], v[232:233]
	s_nop 0
	global_store_dwordx4 v[246:247], v[4:7], off offset:3072
	s_waitcnt vmcnt(15)
	v_pk_mul_f32 v[8:9], v[42:43], v[12:13] op_sel_hi:[1,0]
	v_pk_mul_f32 v[10:11], v[40:41], v[12:13] op_sel_hi:[1,0]
	v_pk_mul_f32 v[8:9], v[8:9], v[234:235]
	v_pk_mul_f32 v[10:11], v[10:11], v[236:237]
	s_nop 0
	global_store_dwordx4 v[246:247], v[8:11], off offset:3088
	s_waitcnt vmcnt(15)
	v_pk_mul_f32 v[4:5], v[38:39], v[12:13] op_sel_hi:[1,0]
	v_pk_mul_f32 v[6:7], v[36:37], v[12:13] op_sel_hi:[1,0]
	v_pk_mul_f32 v[4:5], v[4:5], v[238:239]
	v_pk_mul_f32 v[6:7], v[6:7], v[240:241]
	s_nop 0
	global_store_dwordx4 v[246:247], v[4:7], off offset:3104
	s_waitcnt vmcnt(15)
	v_pk_mul_f32 v[8:9], v[34:35], v[12:13] op_sel_hi:[1,0]
	v_pk_mul_f32 v[10:11], v[32:33], v[12:13] op_sel_hi:[1,0]
	v_pk_mul_f32 v[8:9], v[8:9], v[242:243]
	v_pk_mul_f32 v[10:11], v[10:11], v[244:245]
	s_nop 0
	global_store_dwordx4 v[246:247], v[8:11], off offset:3120
	v_add_u32_e32 v126, s28, v126
	v_cmp_lt_i32_e64 s[20:21], s30, v126
	s_or_b64 s[24:25], s[20:21], s[24:25]
	s_andn2_b64 exec, exec, s[24:25]
	s_cbranch_execnz .LBB0_496
